# stick-breaking prompt-unit epilogues fully in permuted lane order (O permuted in place, SU loads and OAB stores with permuted addresses), on top of v024
# speedup vs baseline: 1.0200x; 1.0144x over previous
; DEVI unsigned pk_bf16(float lo, float hi) { const f32x2_t v = {lo, hi}; const bf16x2_t b = __builtin_convertvector(v, bf16x2_t); return __builtin_bit_cast(unsigned, b); }
; DEVI float bf_lo(unsigned u) { return __uint_as_float(u << 16); }
; DEVI float bf_hi(unsigned u) { return __uint_as_float(u & 0xffff0000u); }
; DEVI float shx(float v, int m) { return __shfl_xor(v, m); }
; template <int MODE, bool SAMPLE>
; DEVI void attn_unit(const Params& p, const int b, const int h, const int qt, unsigned char* smem) {
;     ...
;     if (active) {
;         const bf16_t* SU = (const bf16_t*)(p.ws + (MODE == 0 ? W_SUA : W_SUB));
;         bf16_t* OAB = (bf16_t*)(p.ws + W_OAB);
; #pragma unroll
;         for (int j = 0; j < 2; ++j) {
;             float inv = 1.0f;
;             if (MODE == 0) { float l = st_l[j]; l += shx(l, 16); l += shx(l, 32); inv = (l > 0.f) ? __builtin_amdgcn_rcpf(l) : 0.f; }
;             const int tok = tok0 + 16 * j + l15;
; #pragma unroll
;             for (int dt = 0; dt < 4; ++dt) {
;                 const int col = h * 64 + 16 * dt + 4 * g;
;                 const u32x2 su = *(const u32x2*)(SU + (size_t)tok * 512 + col);
;                 f32x4 o = O[dt][j] * inv;
;                 u32x2 ov; ov.x = pk_bf16(o[0] * bf_lo(su.x), o[1] * bf_hi(su.x)); ov.y = pk_bf16(o[2] * bf_lo(su.y), o[3] * bf_hi(su.y));
;                 *(u32x2*)(OAB + (MODE == 0 ? (size_t)0 : (size_t)NTOK * 512) + (size_t)tok * 512 + col) = ov;
;             }
.LBB0_758:
	s_or_b64 exec, exec, s[58:59]
	v_and_b32_e32 v250, 63, v203
	v_and_b32_e32 v251, 3, v250
	v_lshrrev_b32_e32 v252, 4, v250
	v_bfe_u32 v253, v250, 2, 2
	v_lshl_add_u32 v252, v252, 2, v253
	v_lshl_add_u32 v250, v251, 4, v252
	v_lshlrev_b32_e32 v250, 2, v250
	v_or_b32_e32 v0, s73, v158
	v_lshl_add_u64 v[2:3], s[52:53], 0, v[70:71]
	v_lshlrev_b32_e32 v0, 1, v0
	v_lshl_add_u64 v[2:3], v[2:3], 0, v[0:1]
	ds_bpermute_b32 v246, v250, v2
	ds_bpermute_b32 v247, v250, v3
	s_waitcnt lgkmcnt(0)
	global_load_dwordx2 v[8:9], v[246:247], off
	global_load_dwordx2 v[10:11], v[246:247], off offset:32
	global_load_dwordx2 v[12:13], v[246:247], off offset:64
	s_nop 0
	global_load_dwordx2 v[2:3], v[246:247], off offset:96
	v_lshl_add_u64 v[14:15], s[52:53], 0, v[72:73]
	v_lshl_add_u64 v[14:15], v[14:15], 0, v[0:1]
	ds_bpermute_b32 v248, v250, v14
	ds_bpermute_b32 v249, v250, v15
	s_waitcnt lgkmcnt(0)
	global_load_dwordx2 v[16:17], v[248:249], off
	global_load_dwordx2 v[18:19], v[248:249], off offset:32
	global_load_dwordx2 v[20:21], v[248:249], off offset:64
	s_nop 0
	global_load_dwordx2 v[14:15], v[248:249], off offset:96
	v_lshl_add_u64 v[22:23], s[54:55], 0, v[70:71]
	v_lshl_add_u64 v[52:53], s[54:55], 0, v[72:73]
	v_lshl_add_u64 v[22:23], v[22:23], 0, v[0:1]
	s_add_u32 s0, s56, 0xc0
	v_lshl_add_u64 v[52:53], v[52:53], 0, v[0:1]
	s_addc_u32 s1, s57, 0
	s_addk_i32 s70, 0x300
	s_cmpk_gt_i32 s56, 0x33f
	s_mov_b64 s[56:57], s[0:1]
	ds_bpermute_b32 v4, v250, v4
	ds_bpermute_b32 v5, v250, v5
	ds_bpermute_b32 v6, v250, v6
	ds_bpermute_b32 v7, v250, v7
	ds_bpermute_b32 v24, v250, v24
	ds_bpermute_b32 v25, v250, v25
	ds_bpermute_b32 v26, v250, v26
	ds_bpermute_b32 v27, v250, v27
	ds_bpermute_b32 v28, v250, v28
	ds_bpermute_b32 v29, v250, v29
	ds_bpermute_b32 v30, v250, v30
	s_waitcnt lgkmcnt(0)
	ds_bpermute_b32 v31, v250, v31
	ds_bpermute_b32 v32, v250, v32
	ds_bpermute_b32 v33, v250, v33
	ds_bpermute_b32 v34, v250, v34
	ds_bpermute_b32 v35, v250, v35
	ds_bpermute_b32 v36, v250, v36
	ds_bpermute_b32 v37, v250, v37
	ds_bpermute_b32 v38, v250, v38
	ds_bpermute_b32 v39, v250, v39
	ds_bpermute_b32 v40, v250, v40
	ds_bpermute_b32 v41, v250, v41
	s_waitcnt lgkmcnt(0)
	ds_bpermute_b32 v42, v250, v42
	ds_bpermute_b32 v43, v250, v43
	ds_bpermute_b32 v44, v250, v44
	ds_bpermute_b32 v45, v250, v45
	ds_bpermute_b32 v46, v250, v46
	ds_bpermute_b32 v47, v250, v47
	ds_bpermute_b32 v48, v250, v48
	ds_bpermute_b32 v49, v250, v49
	ds_bpermute_b32 v50, v250, v50
	ds_bpermute_b32 v51, v250, v51
	s_waitcnt lgkmcnt(0)
	s_waitcnt vmcnt(7)
	v_lshlrev_b32_e32 v54, 16, v8
	v_and_b32_e32 v55, 0xffff0000, v8
	v_lshlrev_b32_e32 v8, 16, v9
	v_and_b32_e32 v9, 0xffff0000, v9
	s_waitcnt vmcnt(6)
	v_lshlrev_b32_e32 v56, 16, v10
	v_and_b32_e32 v57, 0xffff0000, v10
	v_lshlrev_b32_e32 v10, 16, v11
	v_and_b32_e32 v11, 0xffff0000, v11
	s_waitcnt vmcnt(5)
	v_lshlrev_b32_e32 v58, 16, v12
	v_and_b32_e32 v59, 0xffff0000, v12
	v_lshlrev_b32_e32 v12, 16, v13
	v_and_b32_e32 v13, 0xffff0000, v13
	s_waitcnt vmcnt(4)
	v_lshlrev_b32_e32 v60, 16, v2
	v_and_b32_e32 v61, 0xffff0000, v2
	v_lshlrev_b32_e32 v2, 16, v3
	v_and_b32_e32 v3, 0xffff0000, v3
	s_waitcnt vmcnt(3)
	v_lshlrev_b32_e32 v62, 16, v16
	v_and_b32_e32 v63, 0xffff0000, v16
	v_lshlrev_b32_e32 v16, 16, v17
	v_and_b32_e32 v17, 0xffff0000, v17
	s_waitcnt vmcnt(2)
	v_lshlrev_b32_e32 v64, 16, v18
	v_and_b32_e32 v65, 0xffff0000, v18
	v_lshlrev_b32_e32 v18, 16, v19
	v_and_b32_e32 v19, 0xffff0000, v19
	s_waitcnt vmcnt(1)
	v_lshlrev_b32_e32 v66, 16, v20
	v_and_b32_e32 v67, 0xffff0000, v20
	v_lshlrev_b32_e32 v20, 16, v21
	v_and_b32_e32 v21, 0xffff0000, v21
	v_pk_mul_f32 v[48:49], v[48:49], v[54:55]
	v_pk_mul_f32 v[8:9], v[50:51], v[8:9]
	v_pk_mul_f32 v[10:11], v[42:43], v[10:11]
	v_pk_mul_f32 v[12:13], v[38:39], v[12:13]
	v_pk_mul_f32 v[2:3], v[34:35], v[2:3]
	v_pk_mul_f32 v[34:35], v[44:45], v[62:63]
	v_pk_mul_f32 v[16:17], v[46:47], v[16:17]
	s_waitcnt vmcnt(0)
	v_lshlrev_b32_e32 v70, 16, v14
	v_and_b32_e32 v71, 0xffff0000, v14
	v_lshlrev_b32_e32 v14, 16, v15
	v_and_b32_e32 v15, 0xffff0000, v15
	v_pk_mul_f32 v[40:41], v[40:41], v[56:57]
	v_pk_mul_f32 v[36:37], v[36:37], v[58:59]
	v_pk_mul_f32 v[32:33], v[32:33], v[60:61]
	v_pk_mul_f32 v[28:29], v[28:29], v[64:65]
	v_pk_mul_f32 v[18:19], v[30:31], v[18:19]
	v_pk_mul_f32 v[24:25], v[24:25], v[66:67]
	v_pk_mul_f32 v[20:21], v[26:27], v[20:21]
	v_cvt_pk_bf16_f32 v26, v48, v49
	v_cvt_pk_bf16_f32 v27, v8, v9
	v_cvt_pk_bf16_f32 v9, v10, v11
	v_cvt_pk_bf16_f32 v11, v12, v13
	v_cvt_pk_bf16_f32 v13, v2, v3
	v_cvt_pk_bf16_f32 v2, v34, v35
	v_cvt_pk_bf16_f32 v3, v16, v17
	v_pk_mul_f32 v[4:5], v[4:5], v[70:71]
	v_cvt_pk_bf16_f32 v8, v40, v41
	v_cvt_pk_bf16_f32 v10, v36, v37
	v_cvt_pk_bf16_f32 v12, v32, v33
	v_cvt_pk_bf16_f32 v16, v28, v29
	v_cvt_pk_bf16_f32 v17, v18, v19
	v_cvt_pk_bf16_f32 v18, v24, v25
	v_cvt_pk_bf16_f32 v19, v20, v21
	ds_bpermute_b32 v246, v250, v22
	ds_bpermute_b32 v247, v250, v23
	s_waitcnt lgkmcnt(0)
	global_store_dwordx2 v[246:247], v[26:27], off
	global_store_dwordx2 v[246:247], v[8:9], off offset:32
	global_store_dwordx2 v[246:247], v[10:11], off offset:64
	global_store_dwordx2 v[246:247], v[12:13], off offset:96
	ds_bpermute_b32 v248, v250, v52
	ds_bpermute_b32 v249, v250, v53
	s_waitcnt lgkmcnt(0)
	global_store_dwordx2 v[248:249], v[2:3], off
	global_store_dwordx2 v[248:249], v[16:17], off offset:32
	global_store_dwordx2 v[248:249], v[18:19], off offset:64
	v_pk_mul_f32 v[2:3], v[6:7], v[14:15]
	v_cvt_pk_bf16_f32 v4, v4, v5
	v_cvt_pk_bf16_f32 v5, v2, v3
	global_store_dwordx2 v[248:249], v[4:5], off offset:96
	s_barrier
	s_cbranch_scc1 .LBB0_781

; DEVI unsigned pk_bf16(float lo, float hi) { const f32x2_t v = {lo, hi}; const bf16x2_t b = __builtin_convertvector(v, bf16x2_t); return __builtin_bit_cast(unsigned, b); }
; DEVI float bf_lo(unsigned u) { return __uint_as_float(u << 16); }
; DEVI float bf_hi(unsigned u) { return __uint_as_float(u & 0xffff0000u); }
; DEVI float shx(float v, int m) { return __shfl_xor(v, m); }
; template <int MODE, bool SAMPLE>
; DEVI void attn_unit(const Params& p, const int b, const int h, const int qt, unsigned char* smem) {
;     ...
;     if (active) {
;         const bf16_t* SU = (const bf16_t*)(p.ws + (MODE == 0 ? W_SUA : W_SUB));
;         bf16_t* OAB = (bf16_t*)(p.ws + W_OAB);
; #pragma unroll
;         for (int j = 0; j < 2; ++j) {
;             float inv = 1.0f;
;             if (MODE == 0) { float l = st_l[j]; l += shx(l, 16); l += shx(l, 32); inv = (l > 0.f) ? __builtin_amdgcn_rcpf(l) : 0.f; }
;             const int tok = tok0 + 16 * j + l15;
; #pragma unroll
;             for (int dt = 0; dt < 4; ++dt) {
;                 const int col = h * 64 + 16 * dt + 4 * g;
;                 const u32x2 su = *(const u32x2*)(SU + (size_t)tok * 512 + col);
;                 f32x4 o = O[dt][j] * inv;
;                 u32x2 ov; ov.x = pk_bf16(o[0] * bf_lo(su.x), o[1] * bf_hi(su.x)); ov.y = pk_bf16(o[2] * bf_lo(su.y), o[3] * bf_hi(su.y));
;                 *(u32x2*)(OAB + (MODE == 0 ? (size_t)0 : (size_t)NTOK * 512) + (size_t)tok * 512 + col) = ov;
;             }
.LBB0_784:
	s_or_b64 exec, exec, s[54:55]
	v_and_b32_e32 v250, 63, v203
	v_and_b32_e32 v251, 3, v250
	v_lshrrev_b32_e32 v252, 4, v250
	v_bfe_u32 v253, v250, 2, 2
	v_lshl_add_u32 v252, v252, 2, v253
	v_lshl_add_u32 v250, v251, 4, v252
	v_lshlrev_b32_e32 v250, 2, v250
	v_or_b32_e32 v0, s66, v158
	v_lshl_add_u64 v[2:3], s[50:51], 0, v[70:71]
	v_lshlrev_b32_e32 v0, 1, v0
	v_lshl_add_u64 v[2:3], v[2:3], 0, v[0:1]
	ds_bpermute_b32 v246, v250, v2
	ds_bpermute_b32 v247, v250, v3
	s_waitcnt lgkmcnt(0)
	global_load_dwordx2 v[8:9], v[246:247], off
	global_load_dwordx2 v[10:11], v[246:247], off offset:32
	global_load_dwordx2 v[12:13], v[246:247], off offset:64
	s_nop 0
	global_load_dwordx2 v[2:3], v[246:247], off offset:96
	v_lshl_add_u64 v[14:15], s[50:51], 0, v[72:73]
	v_lshl_add_u64 v[14:15], v[14:15], 0, v[0:1]
	ds_bpermute_b32 v248, v250, v14
	ds_bpermute_b32 v249, v250, v15
	s_waitcnt lgkmcnt(0)
	global_load_dwordx2 v[16:17], v[248:249], off
	global_load_dwordx2 v[18:19], v[248:249], off offset:32
	global_load_dwordx2 v[20:21], v[248:249], off offset:64
	s_nop 0
	global_load_dwordx2 v[14:15], v[248:249], off offset:96
	v_lshl_add_u64 v[22:23], s[52:53], 0, v[70:71]
	v_lshl_add_u64 v[52:53], s[52:53], 0, v[72:73]
	v_lshl_add_u64 v[22:23], v[22:23], 0, v[0:1]
	v_lshl_add_u64 v[52:53], v[52:53], 0, v[0:1]
	s_add_i32 s0, s60, 1
	s_add_i32 s93, s93, 4
	s_cmp_eq_u32 s60, s2
	s_mov_b32 s60, s0
	ds_bpermute_b32 v4, v250, v4
	ds_bpermute_b32 v5, v250, v5
	ds_bpermute_b32 v6, v250, v6
	ds_bpermute_b32 v7, v250, v7
	ds_bpermute_b32 v24, v250, v24
	ds_bpermute_b32 v25, v250, v25
	ds_bpermute_b32 v26, v250, v26
	ds_bpermute_b32 v27, v250, v27
	ds_bpermute_b32 v28, v250, v28
	ds_bpermute_b32 v29, v250, v29
	ds_bpermute_b32 v30, v250, v30
	s_waitcnt lgkmcnt(0)
	ds_bpermute_b32 v31, v250, v31
	ds_bpermute_b32 v32, v250, v32
	ds_bpermute_b32 v33, v250, v33
	ds_bpermute_b32 v34, v250, v34
	ds_bpermute_b32 v35, v250, v35
	ds_bpermute_b32 v36, v250, v36
	ds_bpermute_b32 v37, v250, v37
	ds_bpermute_b32 v38, v250, v38
	ds_bpermute_b32 v39, v250, v39
	ds_bpermute_b32 v40, v250, v40
	ds_bpermute_b32 v41, v250, v41
	s_waitcnt lgkmcnt(0)
	ds_bpermute_b32 v42, v250, v42
	ds_bpermute_b32 v43, v250, v43
	ds_bpermute_b32 v44, v250, v44
	ds_bpermute_b32 v45, v250, v45
	ds_bpermute_b32 v46, v250, v46
	ds_bpermute_b32 v47, v250, v47
	ds_bpermute_b32 v48, v250, v48
	ds_bpermute_b32 v49, v250, v49
	ds_bpermute_b32 v50, v250, v50
	ds_bpermute_b32 v51, v250, v51
	s_waitcnt lgkmcnt(0)
	s_waitcnt vmcnt(7)
	v_lshlrev_b32_e32 v54, 16, v8
	v_and_b32_e32 v55, 0xffff0000, v8
	v_lshlrev_b32_e32 v8, 16, v9
	v_and_b32_e32 v9, 0xffff0000, v9
	s_waitcnt vmcnt(6)
	v_lshlrev_b32_e32 v56, 16, v10
	v_and_b32_e32 v57, 0xffff0000, v10
	v_lshlrev_b32_e32 v10, 16, v11
	v_and_b32_e32 v11, 0xffff0000, v11
	s_waitcnt vmcnt(5)
	v_lshlrev_b32_e32 v58, 16, v12
	v_and_b32_e32 v59, 0xffff0000, v12
	v_lshlrev_b32_e32 v12, 16, v13
	v_and_b32_e32 v13, 0xffff0000, v13
	s_waitcnt vmcnt(4)
	v_lshlrev_b32_e32 v60, 16, v2
	v_and_b32_e32 v61, 0xffff0000, v2
	v_lshlrev_b32_e32 v2, 16, v3
	v_and_b32_e32 v3, 0xffff0000, v3
	s_waitcnt vmcnt(3)
	v_lshlrev_b32_e32 v62, 16, v16
	v_and_b32_e32 v63, 0xffff0000, v16
	v_lshlrev_b32_e32 v16, 16, v17
	v_and_b32_e32 v17, 0xffff0000, v17
	s_waitcnt vmcnt(2)
	v_lshlrev_b32_e32 v64, 16, v18
	v_and_b32_e32 v65, 0xffff0000, v18
	v_lshlrev_b32_e32 v18, 16, v19
	v_and_b32_e32 v19, 0xffff0000, v19
	s_waitcnt vmcnt(1)
	v_lshlrev_b32_e32 v66, 16, v20
	v_and_b32_e32 v67, 0xffff0000, v20
	v_lshlrev_b32_e32 v20, 16, v21
	v_and_b32_e32 v21, 0xffff0000, v21
	v_pk_mul_f32 v[48:49], v[48:49], v[54:55]
	v_pk_mul_f32 v[8:9], v[50:51], v[8:9]
	v_pk_mul_f32 v[10:11], v[42:43], v[10:11]
	v_pk_mul_f32 v[12:13], v[38:39], v[12:13]
	v_pk_mul_f32 v[2:3], v[34:35], v[2:3]
	v_pk_mul_f32 v[34:35], v[44:45], v[62:63]
	v_pk_mul_f32 v[16:17], v[46:47], v[16:17]
	s_waitcnt vmcnt(0)
	v_lshlrev_b32_e32 v70, 16, v14
	v_and_b32_e32 v71, 0xffff0000, v14
	v_lshlrev_b32_e32 v14, 16, v15
	v_and_b32_e32 v15, 0xffff0000, v15
	v_pk_mul_f32 v[40:41], v[40:41], v[56:57]
	v_pk_mul_f32 v[36:37], v[36:37], v[58:59]
	v_pk_mul_f32 v[32:33], v[32:33], v[60:61]
	v_pk_mul_f32 v[28:29], v[28:29], v[64:65]
	v_pk_mul_f32 v[18:19], v[30:31], v[18:19]
	v_pk_mul_f32 v[24:25], v[24:25], v[66:67]
	v_pk_mul_f32 v[20:21], v[26:27], v[20:21]
	v_cvt_pk_bf16_f32 v26, v48, v49
	v_cvt_pk_bf16_f32 v27, v8, v9
	v_cvt_pk_bf16_f32 v9, v10, v11
	v_cvt_pk_bf16_f32 v11, v12, v13
	v_cvt_pk_bf16_f32 v13, v2, v3
	v_cvt_pk_bf16_f32 v2, v34, v35
	v_cvt_pk_bf16_f32 v3, v16, v17
	v_pk_mul_f32 v[4:5], v[4:5], v[70:71]
	v_cvt_pk_bf16_f32 v8, v40, v41
	v_cvt_pk_bf16_f32 v10, v36, v37
	v_cvt_pk_bf16_f32 v12, v32, v33
	v_cvt_pk_bf16_f32 v16, v28, v29
	v_cvt_pk_bf16_f32 v17, v18, v19
	v_cvt_pk_bf16_f32 v18, v24, v25
	v_cvt_pk_bf16_f32 v19, v20, v21
	ds_bpermute_b32 v246, v250, v22
	ds_bpermute_b32 v247, v250, v23
	s_waitcnt lgkmcnt(0)
	global_store_dwordx2 v[246:247], v[26:27], off
	global_store_dwordx2 v[246:247], v[8:9], off offset:32
	global_store_dwordx2 v[246:247], v[10:11], off offset:64
	global_store_dwordx2 v[246:247], v[12:13], off offset:96
	ds_bpermute_b32 v248, v250, v52
	ds_bpermute_b32 v249, v250, v53
	s_waitcnt lgkmcnt(0)
	global_store_dwordx2 v[248:249], v[2:3], off
	global_store_dwordx2 v[248:249], v[16:17], off offset:32
	global_store_dwordx2 v[248:249], v[18:19], off offset:64
	v_pk_mul_f32 v[2:3], v[6:7], v[14:15]
	v_cvt_pk_bf16_f32 v4, v4, v5
	v_cvt_pk_bf16_f32 v5, v2, v3
	global_store_dwordx2 v[248:249], v[4:5], off offset:96
	s_barrier
	s_cbranch_scc1 .LBB0_807
